# v28
# speedup vs baseline: 1.0108x; 1.0031x over previous
; __device__ __forceinline__ unsigned xb_ld(unsigned* p)              { return __hip_atomic_load(p, __ATOMIC_RELAXED, __HIP_MEMORY_SCOPE_AGENT); }
; __device__ __forceinline__ unsigned xb_add(unsigned* p, unsigned v) { return __hip_atomic_fetch_add(p, v, __ATOMIC_RELAXED, __HIP_MEMORY_SCOPE_AGENT); }
; #define XB_SPIN(cond, bar) do { unsigned _sp = 0; while (cond) { __builtin_amdgcn_s_sleep(1); \
;     if ((++_sp & 255u) == 0u) { if (xb_ld(&(bar)[XB_TMO])) break; if (_sp > XB_SPIN_CAP) { atomicAdd(&(bar)[XB_TMO], 1u); break; } } } } while (0)
; __device__ __forceinline__ void xcd_barrier(const XcdBarrier& b) {
;     ...
;     if (threadIdx.x == 0) {
;         unsigned* bar = b.bar;
;         __builtin_amdgcn_s_waitcnt(0);
;         unsigned nloc = b.st[0], nx = b.st[1];
;         if (nloc == 0u) { xcd_barrier_complete(bar, b.x, nloc, nx); b.st[0] = nloc; b.st[1] = nx; }
;         const unsigned old = xb_add(&bar[XB_XSUB(b.x)], 1u);
;         const unsigned gen = old / nloc;
;         if (old + 1u == (gen + 1u) * nloc) {
;             __builtin_amdgcn_fence(__ATOMIC_RELEASE, "agent");
;             asm volatile("s_waitcnt vmcnt(0)" ::: "memory");
;             const unsigned og = xb_add(&bar[XB_TOP], 1u);
;             const unsigned tg = og / nx;
;             if (og + 1u == (tg + 1u) * nx) xb_add(&bar[XB_TOPGEN], 1u);
;             else XB_SPIN(xb_ld(&bar[XB_TOPGEN]) == tg, bar);
.Llb_go_2:
	s_and_b32 s16, s2, 7
	s_lshl_b32 s16, s16, 8
	s_add_u32 s20, s14, 0x25d05000
	s_addc_u32 s21, s15, 0
	s_add_u32 s20, s20, s16
	s_addc_u32 s21, s21, 0
	v_mov_b32_e32 v2, 0
	v_mov_b32_e32 v3, 1
	global_atomic_add v4, v2, v3, s[20:21] sc0
	buffer_inv sc1
	s_waitcnt vmcnt(1)
	v_readfirstlane_b32 s17, v4
	s_lshr_b32 s22, s17, 5
	s_add_u32 s17, s17, 1
	s_and_b32 s17, s17, 31
	s_cmp_eq_u32 s17, 0
	s_cbranch_scc0 .Llb_wait_2
	global_atomic_add v2, v3, s[20:21] offset:2048
	s_branch .Llb_acq_2

; __device__ __forceinline__ unsigned xb_ld(unsigned* p)              { return __hip_atomic_load(p, __ATOMIC_RELAXED, __HIP_MEMORY_SCOPE_AGENT); }
; __device__ __forceinline__ unsigned xb_add(unsigned* p, unsigned v) { return __hip_atomic_fetch_add(p, v, __ATOMIC_RELAXED, __HIP_MEMORY_SCOPE_AGENT); }
; #define XB_SPIN(cond, bar) do { unsigned _sp = 0; while (cond) { __builtin_amdgcn_s_sleep(1); \
;     if ((++_sp & 255u) == 0u) { if (xb_ld(&(bar)[XB_TMO])) break; if (_sp > XB_SPIN_CAP) { atomicAdd(&(bar)[XB_TMO], 1u); break; } } } } while (0)
; __device__ __forceinline__ void xcd_barrier(const XcdBarrier& b) {
;     ...
;             __builtin_amdgcn_fence(__ATOMIC_ACQUIRE, "agent");
;             xb_add(&bar[XB_XGEN(b.x)], 1u);
;             asm volatile("s_waitcnt vmcnt(0)" ::: "memory");
;         } else {
;             XB_SPIN(xb_ld(&bar[XB_XGEN(b.x)]) == gen, bar);
;             __builtin_amdgcn_fence(__ATOMIC_ACQUIRE, "agent");
;             asm volatile("s_waitcnt vmcnt(0)" ::: "memory");
.Llb_acq_2:
	s_waitcnt vmcnt(0)
	s_branch .LBB0_377

; __device__ __forceinline__ unsigned xb_ld(unsigned* p)              { return __hip_atomic_load(p, __ATOMIC_RELAXED, __HIP_MEMORY_SCOPE_AGENT); }
; __device__ __forceinline__ unsigned xb_add(unsigned* p, unsigned v) { return __hip_atomic_fetch_add(p, v, __ATOMIC_RELAXED, __HIP_MEMORY_SCOPE_AGENT); }
; #define XB_SPIN(cond, bar) do { unsigned _sp = 0; while (cond) { __builtin_amdgcn_s_sleep(1); \
;     if ((++_sp & 255u) == 0u) { if (xb_ld(&(bar)[XB_TMO])) break; if (_sp > XB_SPIN_CAP) { atomicAdd(&(bar)[XB_TMO], 1u); break; } } } } while (0)
; __device__ __forceinline__ void xcd_barrier(const XcdBarrier& b) {
;     ...
;     if (threadIdx.x == 0) {
;         unsigned* bar = b.bar;
;         __builtin_amdgcn_s_waitcnt(0);
;         unsigned nloc = b.st[0], nx = b.st[1];
;         if (nloc == 0u) { xcd_barrier_complete(bar, b.x, nloc, nx); b.st[0] = nloc; b.st[1] = nx; }
;         const unsigned old = xb_add(&bar[XB_XSUB(b.x)], 1u);
;         const unsigned gen = old / nloc;
;         if (old + 1u == (gen + 1u) * nloc) {
;             __builtin_amdgcn_fence(__ATOMIC_RELEASE, "agent");
;             asm volatile("s_waitcnt vmcnt(0)" ::: "memory");
;             const unsigned og = xb_add(&bar[XB_TOP], 1u);
;             const unsigned tg = og / nx;
;             if (og + 1u == (tg + 1u) * nx) xb_add(&bar[XB_TOPGEN], 1u);
;             else XB_SPIN(xb_ld(&bar[XB_TOPGEN]) == tg, bar);
.Llb_go_5:
	s_add_u32 s22, s14, 0x25d06000
	s_addc_u32 s23, s15, 0
	v_mov_b32_e32 v2, 0
	v_mov_b32_e32 v3, 1
	global_atomic_add v2, v3, s[22:23]
	s_and_b32 s16, s2, 7
	s_lshl_b32 s16, s16, 8
	s_add_u32 s20, s14, 0x25d05000
	s_addc_u32 s21, s15, 0
	s_add_u32 s20, s20, s16
	s_addc_u32 s21, s21, 0
	v_mov_b32_e32 v2, 0
	v_mov_b32_e32 v3, 1
	global_atomic_add v4, v2, v3, s[20:21] sc0
	buffer_inv sc1
	s_waitcnt vmcnt(1)
	v_readfirstlane_b32 s17, v4
	s_lshr_b32 s22, s17, 5
	s_add_u32 s17, s17, 1
	s_and_b32 s17, s17, 31
	s_cmp_eq_u32 s17, 0
	s_cbranch_scc0 .Llb_wait_5
	global_atomic_add v2, v3, s[20:21] offset:2048
	s_branch .Llb_acq_5
